# steady attention loops: component-0 softmax runs at priority 1 instead of 0 (MFMA sections stay at 2)
# speedup vs baseline: 1.0318x; 1.0065x over previous
; #define ATT_BAR() do { asm volatile("s_waitcnt lgkmcnt(0)" ::: "memory"); __builtin_amdgcn_s_barrier(); asm volatile("" ::: "memory"); } while (0)
; #define ATT_DMAK(t_, buf_) do { _Pragma("unroll") for (int j = 0; j < 2; ++j) \
;         glds16((const char*)U.K + (size_t)(U.dry ? 0 : (t_)) * (64 * AW * 2) + kdo[j], (unsigned)__builtin_amdgcn_readfirstlane((int)(ldsb + LK + (buf_) + (wid * 2 + j) * 1024))); } while (0)
; #define ATT_DMAV(t_, buf_) do { _Pragma("unroll") for (int j = 0; j < 2; ++j) \
;         glds16((const char*)U.V + (size_t)(U.dry ? 0 : (t_)) * (64 * AW * 2) + vdo[j], (unsigned)__builtin_amdgcn_readfirstlane((int)(ldsb + LV + (buf_) + (wid * 2 + j) * 1024))); } while (0)
; #define ATT_LOADK(t_) do { _Pragma("unroll") for (int i = 0; i < 2; ++i) { \
;         int key = (t_) * 64 + srow + 32 * i; if (key > U.nkeys - 1) key = U.nkeys - 1; \
;         const float* kp = (key < PAST) ? (const float*)U.K + (size_t)key * AW : U.Kn + (size_t)(key - PAST) * AW; \
;         kf4[i][0] = *(const f32x4*)(kp + sch * 8); kf4[i][1] = *(const f32x4*)(kp + sch * 8 + 4); } } while (0)
; #define ATT_WRITEK(buf_) do { _Pragma("unroll") for (int i = 0; i < 2; ++i) *(LAS u32x4*)(lds + LK + (buf_) + kw[i]) = pack8(kf4[i][0], kf4[i][1]); } while (0)
; #define ATT_EVEN(j_, k2_, v1_) do { if (!F32) { if ((j_) + 2 < nt) ATT_DMAK((j_) + 2, k2_); if ((j_) + 1 < nt) ATT_DMAV((j_) + 1, v1_); } } while (0)
; template <bool F32>
; __device__ __forceinline__ void attn_unit(const AUnit& U, LAS unsigned char* lds, float lam, const float* subg) {
;     ...
;     if (!F32) { ATT_DMAK(0, 0); if (nt > 1) ATT_DMAK(1, 16384); ATT_DMAV(0, 0); asm volatile("s_waitcnt vmcnt(0)" ::: "memory"); }
;     else { f32x4 kf4[2][2]; ATT_LOADK(0); ATT_WRITEK(0); }
;     ATT_BAR();
;     int r0 = 32768, r1 = 0, r2 = 16384;
;     if (comp == 0) {
; #pragma unroll 1
;         for (int it = 0; it <= nt; ++it) {
;             ATT_EVEN(it, r0, r2);
;             ATT_MM((it >= 1 && it <= mnt), (it < mnt), r0, r1);
;             if (it < mnt) ATT_SM(it);
;             ATT_ODD(it, r2, r1);
;             ATT_BAR();
;             { const int t_ = r0; r0 = r1; r1 = r2; r2 = t_; }
;         }
.Lc0_st0:
	s_add_u32 s26, s6, 0x1fe0000
	s_addc_u32 s27, s7, 0
	s_mov_b32 m0, s8
	s_nop 0
	global_load_lds_dwordx4 v146, s[6:7]
	s_addk_i32 m0, 0x400
	s_nop 0
	global_load_lds_dwordx4 v148, s[6:7]
	s_add_i32 m0, s28, 0x8000
	s_nop 0
	global_load_lds_dwordx4 v150, s[26:27]
	s_addk_i32 m0, 0x400
	s_nop 0
	global_load_lds_dwordx4 v152, s[26:27]
	ds_read_b64_tr_b16 v[2:3], v0
	ds_read_b64_tr_b16 v[4:5], v14
	ds_read_b64_tr_b16 v[6:7], v15
	ds_read_b64_tr_b16 v[8:9], v171
	ds_read_b64_tr_b16 v[10:11], v180
	ds_read_b64_tr_b16 v[12:13], v181
	ds_read_b64_tr_b16 v[172:173], v253
	ds_read_b64_tr_b16 v[174:175], v254
	ds_read_b64_tr_b16 v[198:199], v0 offset:4096
	ds_read_b64_tr_b16 v[200:201], v14 offset:4096
	ds_read_b64_tr_b16 v[202:203], v15 offset:4096
	ds_read_b64_tr_b16 v[204:205], v171 offset:4096
	ds_read_b64_tr_b16 v[206:207], v180 offset:4096
	ds_read_b64_tr_b16 v[208:209], v181 offset:4096
	s_setprio 2
	s_waitcnt lgkmcnt(12)
	v_mfma_f32_32x32x16_bf16 v[64:79], v[2:5], v[128:131], v[64:79]
	ds_read_b64_tr_b16 v[176:177], v253 offset:4096
	ds_read_b64_tr_b16 v[178:179], v254 offset:4096
	s_waitcnt lgkmcnt(12)
	v_mfma_f32_32x32x16_bf16 v[48:63], v[6:9], v[128:131], v[48:63]
	ds_read_b64_tr_b16 v[2:3], v0 offset:8192
	ds_read_b64_tr_b16 v[4:5], v14 offset:8192
	s_waitcnt lgkmcnt(12)
	v_mfma_f32_32x32x16_bf16 v[32:47], v[10:13], v[128:131], v[32:47]
	ds_read_b64_tr_b16 v[6:7], v15 offset:8192
	ds_read_b64_tr_b16 v[8:9], v171 offset:8192
	s_waitcnt lgkmcnt(12)
	v_mfma_f32_32x32x16_bf16 v[16:31], v[172:175], v[128:131], v[16:31]
	ds_read_b64_tr_b16 v[10:11], v180 offset:8192
	ds_read_b64_tr_b16 v[12:13], v181 offset:8192
	s_waitcnt lgkmcnt(12)
	v_mfma_f32_32x32x16_bf16 v[64:79], v[198:201], v[132:135], v[64:79]
	ds_read_b64_tr_b16 v[172:173], v253 offset:8192
	ds_read_b64_tr_b16 v[174:175], v254 offset:8192
	s_waitcnt lgkmcnt(12)
	v_mfma_f32_32x32x16_bf16 v[48:63], v[202:205], v[132:135], v[48:63]
	ds_read_b64_tr_b16 v[198:199], v0 offset:12288
	ds_read_b64_tr_b16 v[200:201], v14 offset:12288
	s_waitcnt lgkmcnt(12)
	v_mfma_f32_32x32x16_bf16 v[32:47], v[206:209], v[132:135], v[32:47]
	ds_read_b64_tr_b16 v[202:203], v15 offset:12288
	ds_read_b64_tr_b16 v[204:205], v171 offset:12288
	s_waitcnt lgkmcnt(12)
	v_mfma_f32_32x32x16_bf16 v[16:31], v[176:179], v[132:135], v[16:31]
	ds_read_b64_tr_b16 v[206:207], v180 offset:12288
	ds_read_b64_tr_b16 v[208:209], v181 offset:12288
	s_waitcnt lgkmcnt(12)
	v_mfma_f32_32x32x16_bf16 v[64:79], v[2:5], v[136:139], v[64:79]
	ds_read_b64_tr_b16 v[176:177], v253 offset:12288
	ds_read_b64_tr_b16 v[178:179], v254 offset:12288
	s_waitcnt lgkmcnt(12)
	v_mfma_f32_32x32x16_bf16 v[48:63], v[6:9], v[136:139], v[48:63]
	ds_read_b128 v[2:5], v145 offset:16384
	s_waitcnt lgkmcnt(11)
	v_mfma_f32_32x32x16_bf16 v[32:47], v[10:13], v[136:139], v[32:47]
	ds_read_b128 v[6:9], v145 offset:24576
	s_waitcnt lgkmcnt(10)
	v_mfma_f32_32x32x16_bf16 v[16:31], v[172:175], v[136:139], v[16:31]
	ds_read_b128 v[10:13], v159 offset:16384
	s_waitcnt lgkmcnt(9)
	v_mfma_f32_32x32x16_bf16 v[64:79], v[198:201], v[140:143], v[64:79]
	ds_read_b128 v[172:175], v159 offset:24576
	s_waitcnt lgkmcnt(8)
	v_mfma_f32_32x32x16_bf16 v[48:63], v[202:205], v[140:143], v[48:63]
	ds_read_b128 v[198:201], v160 offset:16384
	s_waitcnt lgkmcnt(7)
	v_mfma_f32_32x32x16_bf16 v[32:47], v[206:209], v[140:143], v[32:47]
	ds_read_b128 v[202:205], v160 offset:24576
	s_waitcnt lgkmcnt(6)
	v_mfma_f32_32x32x16_bf16 v[16:31], v[176:179], v[140:143], v[16:31]
	ds_read_b128 v[206:209], v161 offset:16384
	ds_read_b128 v[176:179], v161 offset:24576
	s_waitcnt lgkmcnt(7)
	v_mfma_f32_32x32x16_bf16 v[80:95], v[2:5], v[112:115], 0
	s_waitcnt lgkmcnt(6)
	v_mfma_f32_32x32x16_bf16 v[96:111], v[6:9], v[112:115], 0
	s_waitcnt lgkmcnt(5)
	v_mfma_f32_32x32x16_bf16 v[80:95], v[10:13], v[116:119], v[80:95]
	s_waitcnt lgkmcnt(4)
	v_mfma_f32_32x32x16_bf16 v[96:111], v[172:175], v[116:119], v[96:111]
	s_waitcnt lgkmcnt(3)
	v_mfma_f32_32x32x16_bf16 v[80:95], v[198:201], v[120:123], v[80:95]
	s_waitcnt lgkmcnt(2)
	v_mfma_f32_32x32x16_bf16 v[96:111], v[202:205], v[120:123], v[96:111]
	s_waitcnt lgkmcnt(1)
	v_mfma_f32_32x32x16_bf16 v[80:95], v[206:209], v[124:127], v[80:95]
	s_waitcnt lgkmcnt(0)
	v_mfma_f32_32x32x16_bf16 v[96:111], v[176:179], v[124:127], v[96:111]
	s_setprio 1
	s_add_u32 s6, s6, 0x20000
	s_addc_u32 s7, s7, 0
	s_add_i32 s31, s31, 1
	s_nop 5
	v_exp_f32_e32 v80, v80
	v_exp_f32_e32 v81, v81
	v_exp_f32_e32 v82, v82
	v_exp_f32_e32 v83, v83
	v_exp_f32_e32 v84, v84
	v_exp_f32_e32 v85, v85
	v_exp_f32_e32 v86, v86
	v_exp_f32_e32 v87, v87
	v_add_f32_e32 v2, v80, v84
	v_add_f32_e32 v3, v81, v85
	v_add_f32_e32 v4, v82, v86
	v_add_f32_e32 v5, v83, v87
	v_cvt_pk_bf16_f32 v128, v80, v81
	v_cvt_pk_bf16_f32 v129, v82, v83
	v_exp_f32_e32 v88, v88
	v_exp_f32_e32 v89, v89
	v_exp_f32_e32 v90, v90
	v_exp_f32_e32 v91, v91
	v_cvt_pk_bf16_f32 v130, v84, v85
	v_cvt_pk_bf16_f32 v131, v86, v87
	v_add_f32_e32 v2, v2, v88
	v_add_f32_e32 v3, v3, v89
	v_add_f32_e32 v4, v4, v90
	v_add_f32_e32 v5, v5, v91
	v_exp_f32_e32 v92, v92
	v_exp_f32_e32 v93, v93
	v_exp_f32_e32 v94, v94
	v_exp_f32_e32 v95, v95
	v_cvt_pk_bf16_f32 v132, v88, v89
	v_cvt_pk_bf16_f32 v133, v90, v91
	v_add_f32_e32 v2, v2, v92
	v_add_f32_e32 v3, v3, v93
	v_add_f32_e32 v4, v4, v94
	v_add_f32_e32 v5, v5, v95
	v_exp_f32_e32 v96, v96
	v_exp_f32_e32 v97, v97
	v_exp_f32_e32 v98, v98
	v_exp_f32_e32 v99, v99
	v_cvt_pk_bf16_f32 v134, v92, v93
	v_cvt_pk_bf16_f32 v135, v94, v95
	v_add_f32_e32 v2, v2, v96
	v_add_f32_e32 v3, v3, v97
	v_add_f32_e32 v4, v4, v98
	v_add_f32_e32 v5, v5, v99
	v_exp_f32_e32 v100, v100
	v_exp_f32_e32 v101, v101
	v_exp_f32_e32 v102, v102
	v_exp_f32_e32 v103, v103
	v_cvt_pk_bf16_f32 v136, v96, v97
	v_cvt_pk_bf16_f32 v137, v98, v99
	v_add_f32_e32 v2, v2, v100
	v_add_f32_e32 v3, v3, v101
	v_add_f32_e32 v4, v4, v102
	v_add_f32_e32 v5, v5, v103
	v_exp_f32_e32 v104, v104
	v_exp_f32_e32 v105, v105
	v_exp_f32_e32 v106, v106
	v_exp_f32_e32 v107, v107
	v_cvt_pk_bf16_f32 v138, v100, v101
	v_cvt_pk_bf16_f32 v139, v102, v103
	v_add_f32_e32 v2, v2, v104
	v_add_f32_e32 v3, v3, v105
	v_add_f32_e32 v4, v4, v106
	v_add_f32_e32 v5, v5, v107
	v_exp_f32_e32 v108, v108
	v_exp_f32_e32 v109, v109
	v_exp_f32_e32 v110, v110
	v_exp_f32_e32 v111, v111
	v_cvt_pk_bf16_f32 v140, v104, v105
	v_cvt_pk_bf16_f32 v141, v106, v107
	v_add_f32_e32 v2, v2, v108
	v_add_f32_e32 v3, v3, v109
	v_add_f32_e32 v4, v4, v110
	v_add_f32_e32 v5, v5, v111
	v_add_f32_e32 v2, v2, v3
	v_add_f32_e32 v4, v4, v5
	v_cvt_pk_bf16_f32 v142, v108, v109
	v_add_f32_e32 v2, v2, v4
	v_cvt_pk_bf16_f32 v143, v110, v111
	v_add_f32_e32 v165, v165, v2
	s_waitcnt vmcnt(4)
	s_waitcnt lgkmcnt(0)
	s_barrier
	s_cmp_lt_i32 s31, s94
	s_cbranch_scc1 .Lc0_st1
	s_mov_b32 s22, 0x4000
	s_mov_b32 s29, 0x8000
	s_mov_b32 s30, 0
	s_branch .LBB0_735
; #define ATT_BAR() do { asm volatile("s_waitcnt lgkmcnt(0)" ::: "memory"); __builtin_amdgcn_s_barrier(); asm volatile("" ::: "memory"); } while (0)
; #define ATT_DMAK(t_, buf_) do { _Pragma("unroll") for (int j = 0; j < 2; ++j) \
;         glds16((const char*)U.K + (size_t)(U.dry ? 0 : (t_)) * (64 * AW * 2) + kdo[j], (unsigned)__builtin_amdgcn_readfirstlane((int)(ldsb + LK + (buf_) + (wid * 2 + j) * 1024))); } while (0)
; #define ATT_DMAV(t_, buf_) do { _Pragma("unroll") for (int j = 0; j < 2; ++j) \
;         glds16((const char*)U.V + (size_t)(U.dry ? 0 : (t_)) * (64 * AW * 2) + vdo[j], (unsigned)__builtin_amdgcn_readfirstlane((int)(ldsb + LV + (buf_) + (wid * 2 + j) * 1024))); } while (0)
; #define ATT_LOADK(t_) do { _Pragma("unroll") for (int i = 0; i < 2; ++i) { \
;         int key = (t_) * 64 + srow + 32 * i; if (key > U.nkeys - 1) key = U.nkeys - 1; \
;         const float* kp = (key < PAST) ? (const float*)U.K + (size_t)key * AW : U.Kn + (size_t)(key - PAST) * AW; \
;         kf4[i][0] = *(const f32x4*)(kp + sch * 8); kf4[i][1] = *(const f32x4*)(kp + sch * 8 + 4); } } while (0)
; #define ATT_WRITEK(buf_) do { _Pragma("unroll") for (int i = 0; i < 2; ++i) *(LAS u32x4*)(lds + LK + (buf_) + kw[i]) = pack8(kf4[i][0], kf4[i][1]); } while (0)
; #define ATT_EVEN(j_, k2_, v1_) do { if (!F32) { if ((j_) + 2 < nt) ATT_DMAK((j_) + 2, k2_); if ((j_) + 1 < nt) ATT_DMAV((j_) + 1, v1_); } } while (0)
; template <bool F32>
; __device__ __forceinline__ void attn_unit(const AUnit& U, LAS unsigned char* lds, float lam, const float* subg) {
;     ...
;     if (!F32) { ATT_DMAK(0, 0); if (nt > 1) ATT_DMAK(1, 16384); ATT_DMAV(0, 0); asm volatile("s_waitcnt vmcnt(0)" ::: "memory"); }
;     else { f32x4 kf4[2][2]; ATT_LOADK(0); ATT_WRITEK(0); }
;     ATT_BAR();
;     int r0 = 32768, r1 = 0, r2 = 16384;
;     if (comp == 0) {
; #pragma unroll 1
;         for (int it = 0; it <= nt; ++it) {
;             ATT_EVEN(it, r0, r2);
;             ATT_MM((it >= 1 && it <= mnt), (it < mnt), r0, r1);
;             if (it < mnt) ATT_SM(it);
;             ATT_ODD(it, r2, r1);
;             ATT_BAR();
;             { const int t_ = r0; r0 = r1; r1 = r2; r2 = t_; }
;         }
.Lc0_st1:
	s_add_u32 s26, s6, 0x1fe0000
	s_addc_u32 s27, s7, 0
	s_add_i32 m0, s8, 0x4000
	s_nop 0
	global_load_lds_dwordx4 v146, s[6:7]
	s_addk_i32 m0, 0x400
	s_nop 0
	global_load_lds_dwordx4 v148, s[6:7]
	s_mov_b32 m0, s28
	s_nop 0
	global_load_lds_dwordx4 v150, s[26:27]
	s_addk_i32 m0, 0x400
	s_nop 0
	global_load_lds_dwordx4 v152, s[26:27]
	ds_read_b64_tr_b16 v[2:3], v0 offset:16384
	ds_read_b64_tr_b16 v[4:5], v14 offset:16384
	ds_read_b64_tr_b16 v[6:7], v15 offset:16384
	ds_read_b64_tr_b16 v[8:9], v171 offset:16384
	ds_read_b64_tr_b16 v[10:11], v180 offset:16384
	ds_read_b64_tr_b16 v[12:13], v181 offset:16384
	ds_read_b64_tr_b16 v[172:173], v253 offset:16384
	ds_read_b64_tr_b16 v[174:175], v254 offset:16384
	ds_read_b64_tr_b16 v[198:199], v0 offset:20480
	ds_read_b64_tr_b16 v[200:201], v14 offset:20480
	ds_read_b64_tr_b16 v[202:203], v15 offset:20480
	ds_read_b64_tr_b16 v[204:205], v171 offset:20480
	ds_read_b64_tr_b16 v[206:207], v180 offset:20480
	ds_read_b64_tr_b16 v[208:209], v181 offset:20480
	s_setprio 2
	s_waitcnt lgkmcnt(12)
	v_mfma_f32_32x32x16_bf16 v[64:79], v[2:5], v[128:131], v[64:79]
	ds_read_b64_tr_b16 v[176:177], v253 offset:20480
	ds_read_b64_tr_b16 v[178:179], v254 offset:20480
	s_waitcnt lgkmcnt(12)
	v_mfma_f32_32x32x16_bf16 v[48:63], v[6:9], v[128:131], v[48:63]
	ds_read_b64_tr_b16 v[2:3], v0 offset:24576
	ds_read_b64_tr_b16 v[4:5], v14 offset:24576
	s_waitcnt lgkmcnt(12)
	v_mfma_f32_32x32x16_bf16 v[32:47], v[10:13], v[128:131], v[32:47]
	ds_read_b64_tr_b16 v[6:7], v15 offset:24576
	ds_read_b64_tr_b16 v[8:9], v171 offset:24576
	s_waitcnt lgkmcnt(12)
	v_mfma_f32_32x32x16_bf16 v[16:31], v[172:175], v[128:131], v[16:31]
	ds_read_b64_tr_b16 v[10:11], v180 offset:24576
	ds_read_b64_tr_b16 v[12:13], v181 offset:24576
	s_waitcnt lgkmcnt(12)
	v_mfma_f32_32x32x16_bf16 v[64:79], v[198:201], v[132:135], v[64:79]
	ds_read_b64_tr_b16 v[172:173], v253 offset:24576
	ds_read_b64_tr_b16 v[174:175], v254 offset:24576
	s_waitcnt lgkmcnt(12)
	v_mfma_f32_32x32x16_bf16 v[48:63], v[202:205], v[132:135], v[48:63]
	ds_read_b64_tr_b16 v[198:199], v0 offset:28672
	ds_read_b64_tr_b16 v[200:201], v14 offset:28672
	s_waitcnt lgkmcnt(12)
	v_mfma_f32_32x32x16_bf16 v[32:47], v[206:209], v[132:135], v[32:47]
	ds_read_b64_tr_b16 v[202:203], v15 offset:28672
	ds_read_b64_tr_b16 v[204:205], v171 offset:28672
	s_waitcnt lgkmcnt(12)
	v_mfma_f32_32x32x16_bf16 v[16:31], v[176:179], v[132:135], v[16:31]
	ds_read_b64_tr_b16 v[206:207], v180 offset:28672
	ds_read_b64_tr_b16 v[208:209], v181 offset:28672
	s_waitcnt lgkmcnt(12)
	v_mfma_f32_32x32x16_bf16 v[64:79], v[2:5], v[136:139], v[64:79]
	ds_read_b64_tr_b16 v[176:177], v253 offset:28672
	ds_read_b64_tr_b16 v[178:179], v254 offset:28672
	s_waitcnt lgkmcnt(12)
	v_mfma_f32_32x32x16_bf16 v[48:63], v[6:9], v[136:139], v[48:63]
	ds_read_b128 v[2:5], v145 offset:32768
	s_waitcnt lgkmcnt(11)
	v_mfma_f32_32x32x16_bf16 v[32:47], v[10:13], v[136:139], v[32:47]
	ds_read_b128 v[6:9], v145 offset:40960
	s_waitcnt lgkmcnt(10)
	v_mfma_f32_32x32x16_bf16 v[16:31], v[172:175], v[136:139], v[16:31]
	ds_read_b128 v[10:13], v159 offset:32768
	s_waitcnt lgkmcnt(9)
	v_mfma_f32_32x32x16_bf16 v[64:79], v[198:201], v[140:143], v[64:79]
	ds_read_b128 v[172:175], v159 offset:40960
	s_waitcnt lgkmcnt(8)
	v_mfma_f32_32x32x16_bf16 v[48:63], v[202:205], v[140:143], v[48:63]
	ds_read_b128 v[198:201], v160 offset:32768
	s_waitcnt lgkmcnt(7)
	v_mfma_f32_32x32x16_bf16 v[32:47], v[206:209], v[140:143], v[32:47]
	ds_read_b128 v[202:205], v160 offset:40960
	s_waitcnt lgkmcnt(6)
	v_mfma_f32_32x32x16_bf16 v[16:31], v[176:179], v[140:143], v[16:31]
	ds_read_b128 v[206:209], v161 offset:32768
	ds_read_b128 v[176:179], v161 offset:40960
	s_waitcnt lgkmcnt(7)
	v_mfma_f32_32x32x16_bf16 v[80:95], v[2:5], v[112:115], 0
	s_waitcnt lgkmcnt(6)
	v_mfma_f32_32x32x16_bf16 v[96:111], v[6:9], v[112:115], 0
	s_waitcnt lgkmcnt(5)
	v_mfma_f32_32x32x16_bf16 v[80:95], v[10:13], v[116:119], v[80:95]
	s_waitcnt lgkmcnt(4)
	v_mfma_f32_32x32x16_bf16 v[96:111], v[172:175], v[116:119], v[96:111]
	s_waitcnt lgkmcnt(3)
	v_mfma_f32_32x32x16_bf16 v[80:95], v[198:201], v[120:123], v[80:95]
	s_waitcnt lgkmcnt(2)
	v_mfma_f32_32x32x16_bf16 v[96:111], v[202:205], v[120:123], v[96:111]
	s_waitcnt lgkmcnt(1)
	v_mfma_f32_32x32x16_bf16 v[80:95], v[206:209], v[124:127], v[80:95]
	s_waitcnt lgkmcnt(0)
	v_mfma_f32_32x32x16_bf16 v[96:111], v[176:179], v[124:127], v[96:111]
	s_setprio 1
	s_add_u32 s6, s6, 0x20000
	s_addc_u32 s7, s7, 0
	s_add_i32 s31, s31, 1
	s_nop 5
	v_exp_f32_e32 v80, v80
	v_exp_f32_e32 v81, v81
	v_exp_f32_e32 v82, v82
	v_exp_f32_e32 v83, v83
	v_exp_f32_e32 v84, v84
	v_exp_f32_e32 v85, v85
	v_exp_f32_e32 v86, v86
	v_exp_f32_e32 v87, v87
	v_add_f32_e32 v2, v80, v84
	v_add_f32_e32 v3, v81, v85
	v_add_f32_e32 v4, v82, v86
	v_add_f32_e32 v5, v83, v87
	v_cvt_pk_bf16_f32 v128, v80, v81
	v_cvt_pk_bf16_f32 v129, v82, v83
	v_exp_f32_e32 v88, v88
	v_exp_f32_e32 v89, v89
	v_exp_f32_e32 v90, v90
	v_exp_f32_e32 v91, v91
	v_cvt_pk_bf16_f32 v130, v84, v85
	v_cvt_pk_bf16_f32 v131, v86, v87
	v_add_f32_e32 v2, v2, v88
	v_add_f32_e32 v3, v3, v89
	v_add_f32_e32 v4, v4, v90
	v_add_f32_e32 v5, v5, v91
	v_exp_f32_e32 v92, v92
	v_exp_f32_e32 v93, v93
	v_exp_f32_e32 v94, v94
	v_exp_f32_e32 v95, v95
	v_cvt_pk_bf16_f32 v132, v88, v89
	v_cvt_pk_bf16_f32 v133, v90, v91
	v_add_f32_e32 v2, v2, v92
	v_add_f32_e32 v3, v3, v93
	v_add_f32_e32 v4, v4, v94
	v_add_f32_e32 v5, v5, v95
	v_exp_f32_e32 v96, v96
	v_exp_f32_e32 v97, v97
	v_exp_f32_e32 v98, v98
	v_exp_f32_e32 v99, v99
	v_cvt_pk_bf16_f32 v134, v92, v93
	v_cvt_pk_bf16_f32 v135, v94, v95
	v_add_f32_e32 v2, v2, v96
	v_add_f32_e32 v3, v3, v97
	v_add_f32_e32 v4, v4, v98
	v_add_f32_e32 v5, v5, v99
	v_exp_f32_e32 v100, v100
	v_exp_f32_e32 v101, v101
	v_exp_f32_e32 v102, v102
	v_exp_f32_e32 v103, v103
	v_cvt_pk_bf16_f32 v136, v96, v97
	v_cvt_pk_bf16_f32 v137, v98, v99
	v_add_f32_e32 v2, v2, v100
	v_add_f32_e32 v3, v3, v101
	v_add_f32_e32 v4, v4, v102
	v_add_f32_e32 v5, v5, v103
	v_exp_f32_e32 v104, v104
	v_exp_f32_e32 v105, v105
	v_exp_f32_e32 v106, v106
	v_exp_f32_e32 v107, v107
	v_cvt_pk_bf16_f32 v138, v100, v101
	v_cvt_pk_bf16_f32 v139, v102, v103
	v_add_f32_e32 v2, v2, v104
	v_add_f32_e32 v3, v3, v105
	v_add_f32_e32 v4, v4, v106
	v_add_f32_e32 v5, v5, v107
	v_exp_f32_e32 v108, v108
	v_exp_f32_e32 v109, v109
	v_exp_f32_e32 v110, v110
	v_exp_f32_e32 v111, v111
	v_cvt_pk_bf16_f32 v140, v104, v105
	v_cvt_pk_bf16_f32 v141, v106, v107
	v_add_f32_e32 v2, v2, v108
	v_add_f32_e32 v3, v3, v109
	v_add_f32_e32 v4, v4, v110
	v_add_f32_e32 v5, v5, v111
	v_add_f32_e32 v2, v2, v3
	v_add_f32_e32 v4, v4, v5
	v_cvt_pk_bf16_f32 v142, v108, v109
	v_add_f32_e32 v2, v2, v4
	v_cvt_pk_bf16_f32 v143, v110, v111
	v_add_f32_e32 v165, v165, v2
	s_waitcnt vmcnt(4)
	s_waitcnt lgkmcnt(0)
	s_barrier
	s_cmp_lt_i32 s31, s94
	s_cbranch_scc1 .Lc0_st2
	s_mov_b32 s22, 0x8000
	s_mov_b32 s29, 0
	s_mov_b32 s30, 0x4000
	s_branch .LBB0_735
; #define ATT_BAR() do { asm volatile("s_waitcnt lgkmcnt(0)" ::: "memory"); __builtin_amdgcn_s_barrier(); asm volatile("" ::: "memory"); } while (0)
; #define ATT_DMAK(t_, buf_) do { _Pragma("unroll") for (int j = 0; j < 2; ++j) \
;         glds16((const char*)U.K + (size_t)(U.dry ? 0 : (t_)) * (64 * AW * 2) + kdo[j], (unsigned)__builtin_amdgcn_readfirstlane((int)(ldsb + LK + (buf_) + (wid * 2 + j) * 1024))); } while (0)
; #define ATT_DMAV(t_, buf_) do { _Pragma("unroll") for (int j = 0; j < 2; ++j) \
;         glds16((const char*)U.V + (size_t)(U.dry ? 0 : (t_)) * (64 * AW * 2) + vdo[j], (unsigned)__builtin_amdgcn_readfirstlane((int)(ldsb + LV + (buf_) + (wid * 2 + j) * 1024))); } while (0)
; #define ATT_LOADK(t_) do { _Pragma("unroll") for (int i = 0; i < 2; ++i) { \
;         int key = (t_) * 64 + srow + 32 * i; if (key > U.nkeys - 1) key = U.nkeys - 1; \
;         const float* kp = (key < PAST) ? (const float*)U.K + (size_t)key * AW : U.Kn + (size_t)(key - PAST) * AW; \
;         kf4[i][0] = *(const f32x4*)(kp + sch * 8); kf4[i][1] = *(const f32x4*)(kp + sch * 8 + 4); } } while (0)
; #define ATT_WRITEK(buf_) do { _Pragma("unroll") for (int i = 0; i < 2; ++i) *(LAS u32x4*)(lds + LK + (buf_) + kw[i]) = pack8(kf4[i][0], kf4[i][1]); } while (0)
; #define ATT_EVEN(j_, k2_, v1_) do { if (!F32) { if ((j_) + 2 < nt) ATT_DMAK((j_) + 2, k2_); if ((j_) + 1 < nt) ATT_DMAV((j_) + 1, v1_); } } while (0)
; template <bool F32>
; __device__ __forceinline__ void attn_unit(const AUnit& U, LAS unsigned char* lds, float lam, const float* subg) {
;     ...
;     if (!F32) { ATT_DMAK(0, 0); if (nt > 1) ATT_DMAK(1, 16384); ATT_DMAV(0, 0); asm volatile("s_waitcnt vmcnt(0)" ::: "memory"); }
;     else { f32x4 kf4[2][2]; ATT_LOADK(0); ATT_WRITEK(0); }
;     ATT_BAR();
;     int r0 = 32768, r1 = 0, r2 = 16384;
;     if (comp == 0) {
; #pragma unroll 1
;         for (int it = 0; it <= nt; ++it) {
;             ATT_EVEN(it, r0, r2);
;             ATT_MM((it >= 1 && it <= mnt), (it < mnt), r0, r1);
;             if (it < mnt) ATT_SM(it);
;             ATT_ODD(it, r2, r1);
;             ATT_BAR();
;             { const int t_ = r0; r0 = r1; r1 = r2; r2 = t_; }
;         }
.Lc0_st2:
	s_add_u32 s26, s6, 0x1fe0000
	s_addc_u32 s27, s7, 0
	s_add_i32 m0, s8, 0x8000
	s_nop 0
	global_load_lds_dwordx4 v146, s[6:7]
	s_addk_i32 m0, 0x400
	s_nop 0
	global_load_lds_dwordx4 v148, s[6:7]
	s_add_i32 m0, s28, 0x4000
	s_nop 0
	global_load_lds_dwordx4 v150, s[26:27]
	s_addk_i32 m0, 0x400
	s_nop 0
	global_load_lds_dwordx4 v152, s[26:27]
	ds_read_b64_tr_b16 v[2:3], v0 offset:32768
	ds_read_b64_tr_b16 v[4:5], v14 offset:32768
	ds_read_b64_tr_b16 v[6:7], v15 offset:32768
	ds_read_b64_tr_b16 v[8:9], v171 offset:32768
	ds_read_b64_tr_b16 v[10:11], v180 offset:32768
	ds_read_b64_tr_b16 v[12:13], v181 offset:32768
	ds_read_b64_tr_b16 v[172:173], v253 offset:32768
	ds_read_b64_tr_b16 v[174:175], v254 offset:32768
	ds_read_b64_tr_b16 v[198:199], v0 offset:36864
	ds_read_b64_tr_b16 v[200:201], v14 offset:36864
	ds_read_b64_tr_b16 v[202:203], v15 offset:36864
	ds_read_b64_tr_b16 v[204:205], v171 offset:36864
	ds_read_b64_tr_b16 v[206:207], v180 offset:36864
	ds_read_b64_tr_b16 v[208:209], v181 offset:36864
	s_setprio 2
	s_waitcnt lgkmcnt(12)
	v_mfma_f32_32x32x16_bf16 v[64:79], v[2:5], v[128:131], v[64:79]
	ds_read_b64_tr_b16 v[176:177], v253 offset:36864
	ds_read_b64_tr_b16 v[178:179], v254 offset:36864
	s_waitcnt lgkmcnt(12)
	v_mfma_f32_32x32x16_bf16 v[48:63], v[6:9], v[128:131], v[48:63]
	ds_read_b64_tr_b16 v[2:3], v0 offset:40960
	ds_read_b64_tr_b16 v[4:5], v14 offset:40960
	s_waitcnt lgkmcnt(12)
	v_mfma_f32_32x32x16_bf16 v[32:47], v[10:13], v[128:131], v[32:47]
	ds_read_b64_tr_b16 v[6:7], v15 offset:40960
	ds_read_b64_tr_b16 v[8:9], v171 offset:40960
	s_waitcnt lgkmcnt(12)
	v_mfma_f32_32x32x16_bf16 v[16:31], v[172:175], v[128:131], v[16:31]
	ds_read_b64_tr_b16 v[10:11], v180 offset:40960
	ds_read_b64_tr_b16 v[12:13], v181 offset:40960
	s_waitcnt lgkmcnt(12)
	v_mfma_f32_32x32x16_bf16 v[64:79], v[198:201], v[132:135], v[64:79]
	ds_read_b64_tr_b16 v[172:173], v253 offset:40960
	ds_read_b64_tr_b16 v[174:175], v254 offset:40960
	s_waitcnt lgkmcnt(12)
	v_mfma_f32_32x32x16_bf16 v[48:63], v[202:205], v[132:135], v[48:63]
	ds_read_b64_tr_b16 v[198:199], v0 offset:45056
	ds_read_b64_tr_b16 v[200:201], v14 offset:45056
	s_waitcnt lgkmcnt(12)
	v_mfma_f32_32x32x16_bf16 v[32:47], v[206:209], v[132:135], v[32:47]
	ds_read_b64_tr_b16 v[202:203], v15 offset:45056
	ds_read_b64_tr_b16 v[204:205], v171 offset:45056
	s_waitcnt lgkmcnt(12)
	v_mfma_f32_32x32x16_bf16 v[16:31], v[176:179], v[132:135], v[16:31]
	ds_read_b64_tr_b16 v[206:207], v180 offset:45056
	ds_read_b64_tr_b16 v[208:209], v181 offset:45056
	s_waitcnt lgkmcnt(12)
	v_mfma_f32_32x32x16_bf16 v[64:79], v[2:5], v[136:139], v[64:79]
	ds_read_b64_tr_b16 v[176:177], v253 offset:45056
	ds_read_b64_tr_b16 v[178:179], v254 offset:45056
	s_waitcnt lgkmcnt(12)
	v_mfma_f32_32x32x16_bf16 v[48:63], v[6:9], v[136:139], v[48:63]
	ds_read_b128 v[2:5], v145
	s_waitcnt lgkmcnt(11)
	v_mfma_f32_32x32x16_bf16 v[32:47], v[10:13], v[136:139], v[32:47]
	ds_read_b128 v[6:9], v145 offset:8192
	s_waitcnt lgkmcnt(10)
	v_mfma_f32_32x32x16_bf16 v[16:31], v[172:175], v[136:139], v[16:31]
	ds_read_b128 v[10:13], v159
	s_waitcnt lgkmcnt(9)
	v_mfma_f32_32x32x16_bf16 v[64:79], v[198:201], v[140:143], v[64:79]
	ds_read_b128 v[172:175], v159 offset:8192
	s_waitcnt lgkmcnt(8)
	v_mfma_f32_32x32x16_bf16 v[48:63], v[202:205], v[140:143], v[48:63]
	ds_read_b128 v[198:201], v160
	s_waitcnt lgkmcnt(7)
	v_mfma_f32_32x32x16_bf16 v[32:47], v[206:209], v[140:143], v[32:47]
	ds_read_b128 v[202:205], v160 offset:8192
	s_waitcnt lgkmcnt(6)
	v_mfma_f32_32x32x16_bf16 v[16:31], v[176:179], v[140:143], v[16:31]
	ds_read_b128 v[206:209], v161
	ds_read_b128 v[176:179], v161 offset:8192
	s_waitcnt lgkmcnt(7)
	v_mfma_f32_32x32x16_bf16 v[80:95], v[2:5], v[112:115], 0
	s_waitcnt lgkmcnt(6)
	v_mfma_f32_32x32x16_bf16 v[96:111], v[6:9], v[112:115], 0
	s_waitcnt lgkmcnt(5)
	v_mfma_f32_32x32x16_bf16 v[80:95], v[10:13], v[116:119], v[80:95]
	s_waitcnt lgkmcnt(4)
	v_mfma_f32_32x32x16_bf16 v[96:111], v[172:175], v[116:119], v[96:111]
	s_waitcnt lgkmcnt(3)
	v_mfma_f32_32x32x16_bf16 v[80:95], v[198:201], v[120:123], v[80:95]
	s_waitcnt lgkmcnt(2)
	v_mfma_f32_32x32x16_bf16 v[96:111], v[202:205], v[120:123], v[96:111]
	s_waitcnt lgkmcnt(1)
	v_mfma_f32_32x32x16_bf16 v[80:95], v[206:209], v[124:127], v[80:95]
	s_waitcnt lgkmcnt(0)
	v_mfma_f32_32x32x16_bf16 v[96:111], v[176:179], v[124:127], v[96:111]
	s_setprio 1
	s_add_u32 s6, s6, 0x20000
	s_addc_u32 s7, s7, 0
	s_add_i32 s31, s31, 1
	s_nop 5
	v_exp_f32_e32 v80, v80
	v_exp_f32_e32 v81, v81
	v_exp_f32_e32 v82, v82
	v_exp_f32_e32 v83, v83
	v_exp_f32_e32 v84, v84
	v_exp_f32_e32 v85, v85
	v_exp_f32_e32 v86, v86
	v_exp_f32_e32 v87, v87
	v_add_f32_e32 v2, v80, v84
	v_add_f32_e32 v3, v81, v85
	v_add_f32_e32 v4, v82, v86
	v_add_f32_e32 v5, v83, v87
	v_cvt_pk_bf16_f32 v128, v80, v81
	v_cvt_pk_bf16_f32 v129, v82, v83
	v_exp_f32_e32 v88, v88
	v_exp_f32_e32 v89, v89
	v_exp_f32_e32 v90, v90
	v_exp_f32_e32 v91, v91
	v_cvt_pk_bf16_f32 v130, v84, v85
	v_cvt_pk_bf16_f32 v131, v86, v87
	v_add_f32_e32 v2, v2, v88
	v_add_f32_e32 v3, v3, v89
	v_add_f32_e32 v4, v4, v90
	v_add_f32_e32 v5, v5, v91
	v_exp_f32_e32 v92, v92
	v_exp_f32_e32 v93, v93
	v_exp_f32_e32 v94, v94
	v_exp_f32_e32 v95, v95
	v_cvt_pk_bf16_f32 v132, v88, v89
	v_cvt_pk_bf16_f32 v133, v90, v91
	v_add_f32_e32 v2, v2, v92
	v_add_f32_e32 v3, v3, v93
	v_add_f32_e32 v4, v4, v94
	v_add_f32_e32 v5, v5, v95
	v_exp_f32_e32 v96, v96
	v_exp_f32_e32 v97, v97
	v_exp_f32_e32 v98, v98
	v_exp_f32_e32 v99, v99
	v_cvt_pk_bf16_f32 v134, v92, v93
	v_cvt_pk_bf16_f32 v135, v94, v95
	v_add_f32_e32 v2, v2, v96
	v_add_f32_e32 v3, v3, v97
	v_add_f32_e32 v4, v4, v98
	v_add_f32_e32 v5, v5, v99
	v_exp_f32_e32 v100, v100
	v_exp_f32_e32 v101, v101
	v_exp_f32_e32 v102, v102
	v_exp_f32_e32 v103, v103
	v_cvt_pk_bf16_f32 v136, v96, v97
	v_cvt_pk_bf16_f32 v137, v98, v99
	v_add_f32_e32 v2, v2, v100
	v_add_f32_e32 v3, v3, v101
	v_add_f32_e32 v4, v4, v102
	v_add_f32_e32 v5, v5, v103
	v_exp_f32_e32 v104, v104
	v_exp_f32_e32 v105, v105
	v_exp_f32_e32 v106, v106
	v_exp_f32_e32 v107, v107
	v_cvt_pk_bf16_f32 v138, v100, v101
	v_cvt_pk_bf16_f32 v139, v102, v103
	v_add_f32_e32 v2, v2, v104
	v_add_f32_e32 v3, v3, v105
	v_add_f32_e32 v4, v4, v106
	v_add_f32_e32 v5, v5, v107
	v_exp_f32_e32 v108, v108
	v_exp_f32_e32 v109, v109
	v_exp_f32_e32 v110, v110
	v_exp_f32_e32 v111, v111
	v_cvt_pk_bf16_f32 v140, v104, v105
	v_cvt_pk_bf16_f32 v141, v106, v107
	v_add_f32_e32 v2, v2, v108
	v_add_f32_e32 v3, v3, v109
	v_add_f32_e32 v4, v4, v110
	v_add_f32_e32 v5, v5, v111
	v_add_f32_e32 v2, v2, v3
	v_add_f32_e32 v4, v4, v5
	v_cvt_pk_bf16_f32 v142, v108, v109
	v_add_f32_e32 v2, v2, v4
	v_cvt_pk_bf16_f32 v143, v110, v111
	v_add_f32_e32 v165, v165, v2
	s_waitcnt vmcnt(4)
	s_waitcnt lgkmcnt(0)
	s_barrier
	s_cmp_lt_i32 s31, s94
	s_cbranch_scc1 .Lc0_st0
	s_mov_b32 s22, 0
	s_mov_b32 s29, 0x4000
	s_mov_b32 s30, 0x8000
	s_branch .LBB0_735
